# P5 tile order for the queue version: each workgroup's static first tile = its own P4 tile's coordinates (FLAG_HB wait on its own row block), queue tiles row-major over the remaining 18 columns
# baseline (speedup 1.0000x reference)
.Lq5_nofetch:
	s_or_b64 exec, exec, s[100:101]
	s_sub_i32 s0, s54, 0x100
	s_mul_hi_u32 s34, s0, 0x38e38e39
	s_lshr_b32 s34, s34, 2
	s_mul_i32 s1, s34, 18
	s_sub_i32 s98, s0, s1
	s_add_i32 s98, s98, 4
	s_and_b32 s0, s54, 7
	s_lshl_b32 s0, s0, 3
	s_lshr_b32 s1, s54, 5
	s_or_b32 s0, s0, s1
	s_bfe_u32 s1, s54, 0x20003
	s_cmpk_lt_u32 s54, 0x100
	s_cselect_b32 s34, s0, s34
	s_cselect_b32 s98, s1, s98
	s_cmp_lg_u32 s54, s10
	s_cbranch_scc1 .LBB0_354
	s_and_saveexec_b64 s[36:37], s[2:3]
	s_cbranch_execz .LBB0_353
	s_lshl_b32 s0, s34, 4
	s_ashr_i32 s1, s0, 31
	s_lshl_b64 s[0:1], s[0:1], 2
	s_add_u32 s38, s11, s0
	s_addc_u32 s39, s33, s1
	s_mov_b32 s35, 0x400001
	s_branch .LBB0_346

.Lq5_nowrite:
	s_or_b64 exec, exec, s[100:101]
	s_waitcnt lgkmcnt(0)
	s_barrier
	v_mov_b32_e32 v251, 0x20600
	ds_read_b32 v251, v251
	s_waitcnt lgkmcnt(0)
	v_readfirstlane_b32 s54, v251
	s_nop 3
	s_cmpk_gt_i32 s54, 0x57f
	s_cselect_b64 s[38:39], -1, 0
	s_cmpk_lt_i32 s54, 0x580
	s_cselect_b64 s[0:1], -1, 0
	s_and_b64 s[0:1], s[2:3], s[0:1]
	s_and_saveexec_b64 s[40:41], s[0:1]
	s_cbranch_execz .LBB0_341
	s_sub_i32 s0, s54, 0x100
	s_mul_hi_u32 s0, s0, 0x38e38e39
	s_lshr_b32 s0, s0, 2
	s_and_b32 s1, s54, 7
	s_lshl_b32 s1, s1, 3
	s_lshr_b32 s46, s54, 5
	s_or_b32 s1, s1, s46
	s_cmpk_lt_u32 s54, 0x100
	s_cselect_b32 s0, s1, s0
	s_lshl_b32 s0, s0, 4
	s_ashr_i32 s1, s0, 31
	s_lshl_b64 s[0:1], s[0:1], 2
	s_add_u32 s46, s11, s0
	s_addc_u32 s47, s33, s1
	s_mov_b32 s35, 0x400001
	s_branch .LBB0_365
